# fuse phase-14 rmsnorm+modulate into phase-13 RES epilogue (LDS row sumsq + 4-WG row-block sync), phase 14 empty
# baseline (speedup 1.0000x reference)
.LBB0_54:
.LBB0_58:
	s_mov_b64 s[4:5], 0

.LBB0_63:
	s_or_b64 exec, exec, s[8:9]
	v_lshlrev_b32_e32 v96, 6, v147
	v_lshl_add_u32 v96, v145, 4, v96
	v_lshl_add_u32 v96, v146, 2, v96
	v_lshlrev_b32_e32 v97, 2, v147
	s_ashr_i32 s0, s6, 13
	s_mulk_i32 s0, 0x1800
	s_ashr_i32 s1, s0, 31
	s_lshl_b64 s[0:1], s[0:1], 2
	s_add_u32 s0, s18, s0
	s_addc_u32 s1, s19, s1
	v_lshlrev_b32_e32 v20, 5, v145
	v_lshlrev_b32_e32 v21, 2, v146
	v_or3_b32 v20, v20, v21, s4
	v_lshlrev_b32_e32 v30, 2, v20
	v_add_u32_e32 v21, s6, v147
	v_lshl_add_u32 v31, v21, 12, v30
	global_load_dwordx4 v[26:29], v30, s[0:1]
	global_load_dwordx4 v[138:141], v30, s[0:1] offset:64
	global_load_dwordx4 v[142:145], v30, s[0:1] offset:512
	global_load_dwordx4 v[146:149], v30, s[0:1] offset:576
	v_mov_b32_e32 v20, v31
	global_load_dwordx4 v[150:153], v20, s[58:59]
	global_load_dwordx4 v[154:157], v20, s[58:59] offset:64
	global_load_dwordx4 v[164:167], v20, s[58:59] offset:512
	global_load_dwordx4 v[168:171], v20, s[58:59] offset:576
	v_add_u32_e32 v20, 0x10000, v31
	global_load_dwordx4 v[172:175], v20, s[58:59]
	global_load_dwordx4 v[198:201], v20, s[58:59] offset:64
	global_load_dwordx4 v[202:205], v20, s[58:59] offset:512
	global_load_dwordx4 v[206:209], v20, s[58:59] offset:576
	v_add_u32_e32 v20, 0x20000, v31
	global_load_dwordx4 v[210:213], v20, s[58:59]
	global_load_dwordx4 v[214:217], v20, s[58:59] offset:64
	global_load_dwordx4 v[218:221], v20, s[58:59] offset:512
	global_load_dwordx4 v[222:225], v20, s[58:59] offset:576
	v_add_u32_e32 v20, 0x30000, v31
	global_load_dwordx4 v[226:229], v20, s[58:59]
	global_load_dwordx4 v[232:235], v20, s[58:59] offset:64
	global_load_dwordx4 v[236:239], v20, s[58:59] offset:512
	global_load_dwordx4 v[240:243], v20, s[58:59] offset:576
	v_mov_b32_e32 v252, 0x358637bd
	v_mov_b32_e32 v250, v246
	v_not_b32_e32 v246, 31
	v_mov_b32_e32 v251, 0x7fc00000
	s_waitcnt vmcnt(0)
	v_mov_b32_e32 v20, v31
	v_add_u32_e32 v21, 0x80000, v31
	v_pk_fma_f32 v[134:135], v[134:135], v[26:27], v[150:151]
	v_pk_fma_f32 v[136:137], v[136:137], v[28:29], v[152:153]
	global_store_dwordx4 v20, v[134:137], s[58:59]
	global_load_dwordx4 v[150:153], v21, s[58:59]
	v_pk_fma_f32 v[22:23], v[22:23], v[138:139], v[154:155]
	v_pk_fma_f32 v[24:25], v[24:25], v[140:141], v[156:157]
	global_store_dwordx4 v20, v[22:25], s[58:59] offset:64
	global_load_dwordx4 v[154:157], v21, s[58:59] offset:64
	v_pk_fma_f32 v[4:5], v[4:5], v[142:143], v[164:165]
	v_pk_fma_f32 v[6:7], v[6:7], v[144:145], v[166:167]
	global_store_dwordx4 v20, v[4:7], s[58:59] offset:512
	global_load_dwordx4 v[164:167], v21, s[58:59] offset:512
	v_pk_fma_f32 v[130:131], v[130:131], v[146:147], v[168:169]
	v_pk_fma_f32 v[132:133], v[132:133], v[148:149], v[170:171]
	global_store_dwordx4 v20, v[130:133], s[58:59] offset:576
	global_load_dwordx4 v[168:171], v21, s[58:59] offset:576
	v_add_u32_e32 v20, 0x10000, v31
	v_add_u32_e32 v21, 0x90000, v31
	v_pk_fma_f32 v[126:127], v[126:127], v[26:27], v[172:173]
	v_pk_fma_f32 v[128:129], v[128:129], v[28:29], v[174:175]
	global_store_dwordx4 v20, v[126:129], s[58:59]
	global_load_dwordx4 v[172:175], v21, s[58:59]
	v_pk_fma_f32 v[118:119], v[118:119], v[138:139], v[198:199]
	v_pk_fma_f32 v[120:121], v[120:121], v[140:141], v[200:201]
	global_store_dwordx4 v20, v[118:121], s[58:59] offset:64
	global_load_dwordx4 v[198:201], v21, s[58:59] offset:64
	v_pk_fma_f32 v[122:123], v[122:123], v[142:143], v[202:203]
	v_pk_fma_f32 v[124:125], v[124:125], v[144:145], v[204:205]
	global_store_dwordx4 v20, v[122:125], s[58:59] offset:512
	global_load_dwordx4 v[202:205], v21, s[58:59] offset:512
	v_pk_fma_f32 v[114:115], v[114:115], v[146:147], v[206:207]
	v_pk_fma_f32 v[116:117], v[116:117], v[148:149], v[208:209]
	global_store_dwordx4 v20, v[114:117], s[58:59] offset:576
	global_load_dwordx4 v[206:209], v21, s[58:59] offset:576
	v_add_u32_e32 v20, 0x20000, v31
	v_add_u32_e32 v21, 0xa0000, v31
	v_pk_fma_f32 v[98:99], v[98:99], v[26:27], v[210:211]
	v_pk_fma_f32 v[100:101], v[100:101], v[28:29], v[212:213]
	global_store_dwordx4 v20, v[98:101], s[58:59]
	global_load_dwordx4 v[210:213], v21, s[58:59]
	v_pk_fma_f32 v[102:103], v[102:103], v[138:139], v[214:215]
	v_pk_fma_f32 v[104:105], v[104:105], v[140:141], v[216:217]
	global_store_dwordx4 v20, v[102:105], s[58:59] offset:64
	global_load_dwordx4 v[214:217], v21, s[58:59] offset:64
	v_pk_fma_f32 v[106:107], v[106:107], v[142:143], v[218:219]
	v_pk_fma_f32 v[108:109], v[108:109], v[144:145], v[220:221]
	global_store_dwordx4 v20, v[106:109], s[58:59] offset:512
	global_load_dwordx4 v[218:221], v21, s[58:59] offset:512
	v_pk_fma_f32 v[110:111], v[110:111], v[146:147], v[222:223]
	v_pk_fma_f32 v[112:113], v[112:113], v[148:149], v[224:225]
	global_store_dwordx4 v20, v[110:113], s[58:59] offset:576
	global_load_dwordx4 v[222:225], v21, s[58:59] offset:576
	v_add_u32_e32 v20, 0x30000, v31
	v_add_u32_e32 v21, 0xb0000, v31
	v_pk_fma_f32 v[84:85], v[84:85], v[26:27], v[226:227]
	v_pk_fma_f32 v[86:87], v[86:87], v[28:29], v[228:229]
	global_store_dwordx4 v20, v[84:87], s[58:59]
	global_load_dwordx4 v[226:229], v21, s[58:59]
	v_pk_fma_f32 v[80:81], v[80:81], v[138:139], v[232:233]
	v_pk_fma_f32 v[82:83], v[82:83], v[140:141], v[234:235]
	global_store_dwordx4 v20, v[80:83], s[58:59] offset:64
	global_load_dwordx4 v[232:235], v21, s[58:59] offset:64
	v_pk_fma_f32 v[92:93], v[92:93], v[142:143], v[236:237]
	v_pk_fma_f32 v[94:95], v[94:95], v[144:145], v[238:239]
	global_store_dwordx4 v20, v[92:95], s[58:59] offset:512
	global_load_dwordx4 v[236:239], v21, s[58:59] offset:512
	v_pk_fma_f32 v[88:89], v[88:89], v[146:147], v[240:241]
	v_pk_fma_f32 v[90:91], v[90:91], v[148:149], v[242:243]
	global_store_dwordx4 v20, v[88:91], s[58:59] offset:576
	global_load_dwordx4 v[240:243], v21, s[58:59] offset:576
	v_add_u32_e32 v21, 0x80000, v31
	s_waitcnt vmcnt(30)
	v_pk_fma_f32 v[68:69], v[68:69], v[26:27], v[150:151]
	v_pk_fma_f32 v[70:71], v[70:71], v[28:29], v[152:153]
	global_store_dwordx4 v21, v[68:71], s[58:59]
	s_waitcnt vmcnt(29)
	v_pk_fma_f32 v[64:65], v[64:65], v[138:139], v[154:155]
	v_pk_fma_f32 v[66:67], v[66:67], v[140:141], v[156:157]
	global_store_dwordx4 v21, v[64:67], s[58:59] offset:64
	s_waitcnt vmcnt(28)
	v_pk_fma_f32 v[76:77], v[76:77], v[142:143], v[164:165]
	v_pk_fma_f32 v[78:79], v[78:79], v[144:145], v[166:167]
	global_store_dwordx4 v21, v[76:79], s[58:59] offset:512
	s_waitcnt vmcnt(27)
	v_pk_fma_f32 v[72:73], v[72:73], v[146:147], v[168:169]
	v_pk_fma_f32 v[74:75], v[74:75], v[148:149], v[170:171]
	global_store_dwordx4 v21, v[72:75], s[58:59] offset:576
	v_add_u32_e32 v21, 0x90000, v31
	s_waitcnt vmcnt(26)
	v_pk_fma_f32 v[52:53], v[52:53], v[26:27], v[172:173]
	v_pk_fma_f32 v[54:55], v[54:55], v[28:29], v[174:175]
	global_store_dwordx4 v21, v[52:55], s[58:59]
	s_waitcnt vmcnt(25)
	v_pk_fma_f32 v[48:49], v[48:49], v[138:139], v[198:199]
	v_pk_fma_f32 v[50:51], v[50:51], v[140:141], v[200:201]
	global_store_dwordx4 v21, v[48:51], s[58:59] offset:64
	s_waitcnt vmcnt(24)
	v_pk_fma_f32 v[60:61], v[60:61], v[142:143], v[202:203]
	v_pk_fma_f32 v[62:63], v[62:63], v[144:145], v[204:205]
	global_store_dwordx4 v21, v[60:63], s[58:59] offset:512
	s_waitcnt vmcnt(23)
	v_pk_fma_f32 v[56:57], v[56:57], v[146:147], v[206:207]
	v_pk_fma_f32 v[58:59], v[58:59], v[148:149], v[208:209]
	global_store_dwordx4 v21, v[56:59], s[58:59] offset:576
	v_add_u32_e32 v21, 0xa0000, v31
	s_waitcnt vmcnt(22)
	v_pk_fma_f32 v[44:45], v[44:45], v[26:27], v[210:211]
	v_pk_fma_f32 v[46:47], v[46:47], v[28:29], v[212:213]
	global_store_dwordx4 v21, v[44:47], s[58:59]
	s_waitcnt vmcnt(21)
	v_pk_fma_f32 v[40:41], v[40:41], v[138:139], v[214:215]
	v_pk_fma_f32 v[42:43], v[42:43], v[140:141], v[216:217]
	global_store_dwordx4 v21, v[40:43], s[58:59] offset:64
	s_waitcnt vmcnt(20)
	v_pk_fma_f32 v[36:37], v[36:37], v[142:143], v[218:219]
	v_pk_fma_f32 v[38:39], v[38:39], v[144:145], v[220:221]
	global_store_dwordx4 v21, v[36:39], s[58:59] offset:512
	s_waitcnt vmcnt(19)
	v_pk_fma_f32 v[32:33], v[32:33], v[146:147], v[222:223]
	v_pk_fma_f32 v[34:35], v[34:35], v[148:149], v[224:225]
	global_store_dwordx4 v21, v[32:35], s[58:59] offset:576
	v_add_u32_e32 v21, 0xb0000, v31
	s_waitcnt vmcnt(18)
	v_pk_fma_f32 v[16:17], v[16:17], v[26:27], v[226:227]
	v_pk_fma_f32 v[18:19], v[18:19], v[28:29], v[228:229]
	global_store_dwordx4 v21, v[16:19], s[58:59]
	s_waitcnt vmcnt(17)
	v_pk_fma_f32 v[12:13], v[12:13], v[138:139], v[232:233]
	v_pk_fma_f32 v[14:15], v[14:15], v[140:141], v[234:235]
	global_store_dwordx4 v21, v[12:15], s[58:59] offset:64
	s_waitcnt vmcnt(16)
	v_pk_fma_f32 v[8:9], v[8:9], v[142:143], v[236:237]
	v_pk_fma_f32 v[10:11], v[10:11], v[144:145], v[238:239]
	global_store_dwordx4 v21, v[8:11], s[58:59] offset:512
	s_waitcnt vmcnt(15)
	v_pk_fma_f32 v[0:1], v[0:1], v[146:147], v[240:241]
	v_pk_fma_f32 v[2:3], v[2:3], v[148:149], v[242:243]
	global_store_dwordx4 v21, v[0:3], s[58:59] offset:576
	s_load_dwordx2 s[98:99], s[54:55], 0x30
	s_add_u32 s28, s0, 0x1000
	s_addc_u32 s29, s1, 0
	s_add_u32 s50, s0, 0x2000
	s_addc_u32 s51, s1, 0
	s_waitcnt lgkmcnt(0)
	s_add_u32 s98, s98, 0x3000
	s_addc_u32 s99, s99, 0
	global_load_dwordx4 v[150:153], v30, s[50:51]
	global_load_dwordx4 v[154:157], v30, s[50:51] offset:64
	global_load_dwordx4 v[164:167], v30, s[50:51] offset:512
	global_load_dwordx4 v[168:171], v30, s[50:51] offset:576
	global_load_dwordx4 v[210:213], v30, s[98:99]
	global_load_dwordx4 v[214:217], v30, s[98:99] offset:64
	global_load_dwordx4 v[218:221], v30, s[98:99] offset:512
	global_load_dwordx4 v[222:225], v30, s[98:99] offset:576
	global_load_dwordx4 v[172:175], v30, s[28:29]
	global_load_dwordx4 v[198:201], v30, s[28:29] offset:64
	global_load_dwordx4 v[202:205], v30, s[28:29] offset:512
	global_load_dwordx4 v[206:209], v30, s[28:29] offset:576
	v_pk_mul_f32 v[26:27], v[134:135], v[134:135]
	v_pk_mul_f32 v[28:29], v[126:127], v[126:127]
	v_pk_fma_f32 v[26:27], v[136:137], v[136:137], v[26:27]
	v_pk_fma_f32 v[28:29], v[128:129], v[128:129], v[28:29]
	v_pk_fma_f32 v[26:27], v[22:23], v[22:23], v[26:27]
	v_pk_fma_f32 v[28:29], v[118:119], v[118:119], v[28:29]
	v_pk_fma_f32 v[26:27], v[24:25], v[24:25], v[26:27]
	v_pk_fma_f32 v[28:29], v[120:121], v[120:121], v[28:29]
	v_pk_fma_f32 v[26:27], v[4:5], v[4:5], v[26:27]
	v_pk_fma_f32 v[28:29], v[122:123], v[122:123], v[28:29]
	v_pk_fma_f32 v[26:27], v[6:7], v[6:7], v[26:27]
	v_pk_fma_f32 v[28:29], v[124:125], v[124:125], v[28:29]
	v_pk_fma_f32 v[26:27], v[130:131], v[130:131], v[26:27]
	v_pk_fma_f32 v[28:29], v[114:115], v[114:115], v[28:29]
	v_pk_fma_f32 v[26:27], v[132:133], v[132:133], v[26:27]
	v_pk_fma_f32 v[28:29], v[116:117], v[116:117], v[28:29]
	s_nop 0
	v_add_f32_e32 v138, v26, v27
	v_add_f32_e32 v139, v28, v29
	v_pk_mul_f32 v[26:27], v[98:99], v[98:99]
	v_pk_mul_f32 v[28:29], v[84:85], v[84:85]
	v_pk_fma_f32 v[26:27], v[100:101], v[100:101], v[26:27]
	v_pk_fma_f32 v[28:29], v[86:87], v[86:87], v[28:29]
	v_pk_fma_f32 v[26:27], v[102:103], v[102:103], v[26:27]
	v_pk_fma_f32 v[28:29], v[80:81], v[80:81], v[28:29]
	v_pk_fma_f32 v[26:27], v[104:105], v[104:105], v[26:27]
	v_pk_fma_f32 v[28:29], v[82:83], v[82:83], v[28:29]
	v_pk_fma_f32 v[26:27], v[106:107], v[106:107], v[26:27]
	v_pk_fma_f32 v[28:29], v[92:93], v[92:93], v[28:29]
	v_pk_fma_f32 v[26:27], v[108:109], v[108:109], v[26:27]
	v_pk_fma_f32 v[28:29], v[94:95], v[94:95], v[28:29]
	v_pk_fma_f32 v[26:27], v[110:111], v[110:111], v[26:27]
	v_pk_fma_f32 v[28:29], v[88:89], v[88:89], v[28:29]
	v_pk_fma_f32 v[26:27], v[112:113], v[112:113], v[26:27]
	v_pk_fma_f32 v[28:29], v[90:91], v[90:91], v[28:29]
	s_nop 0
	v_add_f32_e32 v140, v26, v27
	v_add_f32_e32 v141, v28, v29
	v_pk_mul_f32 v[26:27], v[68:69], v[68:69]
	v_pk_mul_f32 v[28:29], v[52:53], v[52:53]
	v_pk_fma_f32 v[26:27], v[70:71], v[70:71], v[26:27]
	v_pk_fma_f32 v[28:29], v[54:55], v[54:55], v[28:29]
	v_pk_fma_f32 v[26:27], v[64:65], v[64:65], v[26:27]
	v_pk_fma_f32 v[28:29], v[48:49], v[48:49], v[28:29]
	v_pk_fma_f32 v[26:27], v[66:67], v[66:67], v[26:27]
	v_pk_fma_f32 v[28:29], v[50:51], v[50:51], v[28:29]
	v_pk_fma_f32 v[26:27], v[76:77], v[76:77], v[26:27]
	v_pk_fma_f32 v[28:29], v[60:61], v[60:61], v[28:29]
	v_pk_fma_f32 v[26:27], v[78:79], v[78:79], v[26:27]
	v_pk_fma_f32 v[28:29], v[62:63], v[62:63], v[28:29]
	v_pk_fma_f32 v[26:27], v[72:73], v[72:73], v[26:27]
	v_pk_fma_f32 v[28:29], v[56:57], v[56:57], v[28:29]
	v_pk_fma_f32 v[26:27], v[74:75], v[74:75], v[26:27]
	v_pk_fma_f32 v[28:29], v[58:59], v[58:59], v[28:29]
	s_nop 0
	v_add_f32_e32 v142, v26, v27
	v_add_f32_e32 v143, v28, v29
	v_pk_mul_f32 v[26:27], v[44:45], v[44:45]
	v_pk_mul_f32 v[28:29], v[16:17], v[16:17]
	v_pk_fma_f32 v[26:27], v[46:47], v[46:47], v[26:27]
	v_pk_fma_f32 v[28:29], v[18:19], v[18:19], v[28:29]
	v_pk_fma_f32 v[26:27], v[40:41], v[40:41], v[26:27]
	v_pk_fma_f32 v[28:29], v[12:13], v[12:13], v[28:29]
	v_pk_fma_f32 v[26:27], v[42:43], v[42:43], v[26:27]
	v_pk_fma_f32 v[28:29], v[14:15], v[14:15], v[28:29]
	v_pk_fma_f32 v[26:27], v[36:37], v[36:37], v[26:27]
	v_pk_fma_f32 v[28:29], v[8:9], v[8:9], v[28:29]
	v_pk_fma_f32 v[26:27], v[38:39], v[38:39], v[26:27]
	v_pk_fma_f32 v[28:29], v[10:11], v[10:11], v[28:29]
	v_pk_fma_f32 v[26:27], v[32:33], v[32:33], v[26:27]
	v_pk_fma_f32 v[28:29], v[0:1], v[0:1], v[28:29]
	v_pk_fma_f32 v[26:27], v[34:35], v[34:35], v[26:27]
	v_pk_fma_f32 v[28:29], v[2:3], v[2:3], v[28:29]
	s_nop 0
	v_add_f32_e32 v144, v26, v27
	v_add_f32_e32 v145, v28, v29
	s_barrier
	ds_write_b32 v96, v138
	ds_write_b32 v96, v139 offset:1024
	ds_write_b32 v96, v140 offset:2048
	ds_write_b32 v96, v141 offset:3072
	ds_write_b32 v96, v142 offset:8192
	ds_write_b32 v96, v143 offset:9216
	ds_write_b32 v96, v144 offset:10240
	ds_write_b32 v96, v145 offset:11264
	s_lshr_b32 s30, s6, 8
	s_lshl_b32 s30, s30, 2
	s_lshl_b32 s3, s4, 8
	s_add_u32 s4, s46, s30
	s_addc_u32 s5, s47, 0
	s_add_u32 s4, s4, 0xdacc200
	s_addc_u32 s5, s5, 0
	s_lshl_b32 s30, s6, 2
	s_add_u32 s0, s44, s30
	s_addc_u32 s1, s45, 0
	s_add_u32 s0, s0, 0x2200000
	s_addc_u32 s1, s1, 0
	s_waitcnt lgkmcnt(0)
	s_barrier
	s_cmp_ge_u32 s48, 0x100
	s_cbranch_scc1 .Lfu_norow
	v_mbcnt_lo_u32_b32 v158, -1, 0
	v_mbcnt_hi_u32_b32 v158, -1, v158
	v_add_u32_e32 v158, s48, v158
	v_lshlrev_b32_e32 v159, 6, v158
	ds_read_b128 v[226:229], v159
	ds_read_b128 v[232:235], v159 offset:16
	ds_read_b128 v[236:239], v159 offset:32
	ds_read_b128 v[240:243], v159 offset:48
	v_lshlrev_b32_e32 v158, 2, v158
	s_waitcnt lgkmcnt(0)
	v_add_u32_e32 v159, s3, v158
	v_pk_add_f32 v[226:227], v[226:227], v[228:229]
	v_pk_add_f32 v[232:233], v[232:233], v[234:235]
	v_pk_add_f32 v[236:237], v[236:237], v[238:239]
	v_pk_add_f32 v[240:241], v[240:241], v[242:243]
	v_pk_add_f32 v[226:227], v[226:227], v[232:233]
	v_pk_add_f32 v[236:237], v[236:237], v[240:241]
	s_nop 0
	v_pk_add_f32 v[226:227], v[226:227], v[236:237]
	s_nop 0
	v_add_f32_e32 v160, v226, v227
	s_nop 0
	global_store_dword v159, v160, s[0:1]
.Lfu_norow:
	s_waitcnt vmcnt(0)
	s_barrier
	v_mov_b32_e32 v244, 0
	s_cmp_lg_u32 s48, 0
	s_cbranch_scc1 .Lfu_nosig
	buffer_wbl2 sc1
	s_waitcnt vmcnt(0)
	v_mov_b32_e32 v245, 1
	s_mov_b64 exec, 1
	global_atomic_add v244, v245, s[4:5]
	s_mov_b64 exec, -1
.Lfu_nosig:
	v_pk_add_f32 v[150:151], v[150:151], 1.0 op_sel_hi:[1,0]
	v_pk_add_f32 v[152:153], v[152:153], 1.0 op_sel_hi:[1,0]
	v_pk_add_f32 v[154:155], v[154:155], 1.0 op_sel_hi:[1,0]
	v_pk_add_f32 v[156:157], v[156:157], 1.0 op_sel_hi:[1,0]
	v_pk_add_f32 v[164:165], v[164:165], 1.0 op_sel_hi:[1,0]
	v_pk_add_f32 v[166:167], v[166:167], 1.0 op_sel_hi:[1,0]
	v_pk_add_f32 v[168:169], v[168:169], 1.0 op_sel_hi:[1,0]
	v_pk_add_f32 v[170:171], v[170:171], 1.0 op_sel_hi:[1,0]
	v_pk_mul_f32 v[150:151], v[210:211], v[150:151]
	v_pk_mul_f32 v[152:153], v[212:213], v[152:153]
	v_pk_mul_f32 v[154:155], v[214:215], v[154:155]
	v_pk_mul_f32 v[156:157], v[216:217], v[156:157]
	v_pk_mul_f32 v[164:165], v[218:219], v[164:165]
	v_pk_mul_f32 v[166:167], v[220:221], v[166:167]
	v_pk_mul_f32 v[168:169], v[222:223], v[168:169]
	v_pk_mul_f32 v[170:171], v[224:225], v[170:171]
	s_mov_b32 s32, 0
.Lfu_spin:
	global_load_dword v245, v244, s[4:5] sc1
	s_add_i32 s32, s32, 1
	s_waitcnt vmcnt(0)
	v_readfirstlane_b32 s30, v245
	s_cmp_ge_u32 s30, 4
	s_cbranch_scc1 .Lfu_go
	s_cmp_gt_u32 s32, 0x40000
	s_cbranch_scc1 .Lfu_go
	s_sleep 2
	s_branch .Lfu_spin
.Lfu_go:
	buffer_inv sc1
	s_cmp_ge_u32 s48, 0x100
	s_cbranch_scc1 .Lfu_norow2
	global_load_dword v226, v158, s[0:1]
	v_add_u32_e32 v159, 0x10000, v158
	global_load_dword v227, v159, s[0:1]
	v_add_u32_e32 v159, 0x20000, v158
	global_load_dword v228, v159, s[0:1]
	v_add_u32_e32 v159, 0x30000, v158
	global_load_dword v229, v159, s[0:1]
	v_mov_b32_e32 v232, 0x3a800000
	s_waitcnt vmcnt(0)
	v_add_f32_e32 v226, v226, v227
	s_nop 0
	v_add_f32_e32 v226, v226, v228
	s_nop 0
	v_add_f32_e32 v226, v226, v229
	s_nop 0
	v_fma_f32 v226, v226, v232, v252
	s_nop 0
	v_mul_f32_e32 v227, 0x4b800000, v226
	v_cmp_gt_f32_e32 vcc, s84, v226
	s_nop 1
	v_cndmask_b32_e32 v226, v226, v227, vcc
	s_nop 0
	v_rsq_f32_e32 v226, v226
	s_nop 1
	v_mul_f32_e32 v227, 0x45800000, v226
	s_nop 0
	v_cndmask_b32_e32 v226, v226, v227, vcc
	s_nop 0
	ds_write_b32 v158, v226 offset:16384
.Lfu_norow2:
	s_waitcnt lgkmcnt(0)
	s_barrier
	ds_read_b32 v226, v97 offset:16384
	ds_read_b32 v228, v97 offset:16448
	ds_read_b32 v232, v97 offset:16512
	ds_read_b32 v234, v97 offset:16576
	ds_read_b32 v236, v97 offset:16896
	ds_read_b32 v238, v97 offset:16960
	ds_read_b32 v240, v97 offset:17024
	ds_read_b32 v242, v97 offset:17088
	v_lshrrev_b32_e32 v31, 1, v31
	s_waitcnt lgkmcnt(7)
	v_mov_b32_e32 v20, v31
	v_pk_mul_f32 v[210:211], v[134:135], v[226:227] op_sel_hi:[1,0]
	v_pk_mul_f32 v[212:213], v[136:137], v[226:227] op_sel_hi:[1,0]
	v_pk_mul_f32 v[214:215], v[22:23], v[226:227] op_sel_hi:[1,0]
	v_pk_mul_f32 v[216:217], v[24:25], v[226:227] op_sel_hi:[1,0]
	v_pk_fma_f32 v[210:211], v[150:151], v[210:211], v[172:173]
	v_pk_fma_f32 v[212:213], v[152:153], v[212:213], v[174:175]
	v_pk_fma_f32 v[214:215], v[154:155], v[214:215], v[198:199]
	v_pk_fma_f32 v[216:217], v[156:157], v[216:217], v[200:201]
	v_cvt_pk_bf16_f32 v210, v210, v211
	v_cvt_pk_bf16_f32 v211, v212, v213
	v_cvt_pk_bf16_f32 v214, v214, v215
	v_cvt_pk_bf16_f32 v215, v216, v217
	global_store_dwordx2 v20, v[210:211], s[44:45]
	global_store_dwordx2 v20, v[214:215], s[44:45] offset:32
	v_pk_mul_f32 v[218:219], v[4:5], v[226:227] op_sel_hi:[1,0]
	v_pk_mul_f32 v[220:221], v[6:7], v[226:227] op_sel_hi:[1,0]
	v_pk_mul_f32 v[222:223], v[130:131], v[226:227] op_sel_hi:[1,0]
	v_pk_mul_f32 v[224:225], v[132:133], v[226:227] op_sel_hi:[1,0]
	v_pk_fma_f32 v[218:219], v[164:165], v[218:219], v[202:203]
	v_pk_fma_f32 v[220:221], v[166:167], v[220:221], v[204:205]
	v_pk_fma_f32 v[222:223], v[168:169], v[222:223], v[206:207]
	v_pk_fma_f32 v[224:225], v[170:171], v[224:225], v[208:209]
	v_cvt_pk_bf16_f32 v218, v218, v219
	v_cvt_pk_bf16_f32 v219, v220, v221
	v_cvt_pk_bf16_f32 v222, v222, v223
	v_cvt_pk_bf16_f32 v223, v224, v225
	global_store_dwordx2 v20, v[218:219], s[44:45] offset:256
	global_store_dwordx2 v20, v[222:223], s[44:45] offset:288
	s_waitcnt lgkmcnt(6)
	v_add_u32_e32 v21, 0x8000, v31
	v_pk_mul_f32 v[210:211], v[126:127], v[228:229] op_sel_hi:[1,0]
	v_pk_mul_f32 v[212:213], v[128:129], v[228:229] op_sel_hi:[1,0]
	v_pk_mul_f32 v[214:215], v[118:119], v[228:229] op_sel_hi:[1,0]
	v_pk_mul_f32 v[216:217], v[120:121], v[228:229] op_sel_hi:[1,0]
	v_pk_fma_f32 v[210:211], v[150:151], v[210:211], v[172:173]
	v_pk_fma_f32 v[212:213], v[152:153], v[212:213], v[174:175]
	v_pk_fma_f32 v[214:215], v[154:155], v[214:215], v[198:199]
	v_pk_fma_f32 v[216:217], v[156:157], v[216:217], v[200:201]
	v_cvt_pk_bf16_f32 v210, v210, v211
	v_cvt_pk_bf16_f32 v211, v212, v213
	v_cvt_pk_bf16_f32 v214, v214, v215
	v_cvt_pk_bf16_f32 v215, v216, v217
	global_store_dwordx2 v21, v[210:211], s[44:45]
	global_store_dwordx2 v21, v[214:215], s[44:45] offset:32
	v_pk_mul_f32 v[218:219], v[122:123], v[228:229] op_sel_hi:[1,0]
	v_pk_mul_f32 v[220:221], v[124:125], v[228:229] op_sel_hi:[1,0]
	v_pk_mul_f32 v[222:223], v[114:115], v[228:229] op_sel_hi:[1,0]
	v_pk_mul_f32 v[224:225], v[116:117], v[228:229] op_sel_hi:[1,0]
	v_pk_fma_f32 v[218:219], v[164:165], v[218:219], v[202:203]
	v_pk_fma_f32 v[220:221], v[166:167], v[220:221], v[204:205]
	v_pk_fma_f32 v[222:223], v[168:169], v[222:223], v[206:207]
	v_pk_fma_f32 v[224:225], v[170:171], v[224:225], v[208:209]
	v_cvt_pk_bf16_f32 v218, v218, v219
	v_cvt_pk_bf16_f32 v219, v220, v221
	v_cvt_pk_bf16_f32 v222, v222, v223
	v_cvt_pk_bf16_f32 v223, v224, v225
	global_store_dwordx2 v21, v[218:219], s[44:45] offset:256
	global_store_dwordx2 v21, v[222:223], s[44:45] offset:288
	s_waitcnt lgkmcnt(5)
	v_add_u32_e32 v20, 0x10000, v31
	v_pk_mul_f32 v[210:211], v[98:99], v[232:233] op_sel_hi:[1,0]
	v_pk_mul_f32 v[212:213], v[100:101], v[232:233] op_sel_hi:[1,0]
	v_pk_mul_f32 v[214:215], v[102:103], v[232:233] op_sel_hi:[1,0]
	v_pk_mul_f32 v[216:217], v[104:105], v[232:233] op_sel_hi:[1,0]
	v_pk_fma_f32 v[210:211], v[150:151], v[210:211], v[172:173]
	v_pk_fma_f32 v[212:213], v[152:153], v[212:213], v[174:175]
	v_pk_fma_f32 v[214:215], v[154:155], v[214:215], v[198:199]
	v_pk_fma_f32 v[216:217], v[156:157], v[216:217], v[200:201]
	v_cvt_pk_bf16_f32 v210, v210, v211
	v_cvt_pk_bf16_f32 v211, v212, v213
	v_cvt_pk_bf16_f32 v214, v214, v215
	v_cvt_pk_bf16_f32 v215, v216, v217
	global_store_dwordx2 v20, v[210:211], s[44:45]
	global_store_dwordx2 v20, v[214:215], s[44:45] offset:32
	v_pk_mul_f32 v[218:219], v[106:107], v[232:233] op_sel_hi:[1,0]
	v_pk_mul_f32 v[220:221], v[108:109], v[232:233] op_sel_hi:[1,0]
	v_pk_mul_f32 v[222:223], v[110:111], v[232:233] op_sel_hi:[1,0]
	v_pk_mul_f32 v[224:225], v[112:113], v[232:233] op_sel_hi:[1,0]
	v_pk_fma_f32 v[218:219], v[164:165], v[218:219], v[202:203]
	v_pk_fma_f32 v[220:221], v[166:167], v[220:221], v[204:205]
	v_pk_fma_f32 v[222:223], v[168:169], v[222:223], v[206:207]
	v_pk_fma_f32 v[224:225], v[170:171], v[224:225], v[208:209]
	v_cvt_pk_bf16_f32 v218, v218, v219
	v_cvt_pk_bf16_f32 v219, v220, v221
	v_cvt_pk_bf16_f32 v222, v222, v223
	v_cvt_pk_bf16_f32 v223, v224, v225
	global_store_dwordx2 v20, v[218:219], s[44:45] offset:256
	global_store_dwordx2 v20, v[222:223], s[44:45] offset:288
	s_waitcnt lgkmcnt(4)
	v_add_u32_e32 v21, 0x18000, v31
	v_pk_mul_f32 v[210:211], v[84:85], v[234:235] op_sel_hi:[1,0]
	v_pk_mul_f32 v[212:213], v[86:87], v[234:235] op_sel_hi:[1,0]
	v_pk_mul_f32 v[214:215], v[80:81], v[234:235] op_sel_hi:[1,0]
	v_pk_mul_f32 v[216:217], v[82:83], v[234:235] op_sel_hi:[1,0]
	v_pk_fma_f32 v[210:211], v[150:151], v[210:211], v[172:173]
	v_pk_fma_f32 v[212:213], v[152:153], v[212:213], v[174:175]
	v_pk_fma_f32 v[214:215], v[154:155], v[214:215], v[198:199]
	v_pk_fma_f32 v[216:217], v[156:157], v[216:217], v[200:201]
	v_cvt_pk_bf16_f32 v210, v210, v211
	v_cvt_pk_bf16_f32 v211, v212, v213
	v_cvt_pk_bf16_f32 v214, v214, v215
	v_cvt_pk_bf16_f32 v215, v216, v217
	global_store_dwordx2 v21, v[210:211], s[44:45]
	global_store_dwordx2 v21, v[214:215], s[44:45] offset:32
	v_pk_mul_f32 v[218:219], v[92:93], v[234:235] op_sel_hi:[1,0]
	v_pk_mul_f32 v[220:221], v[94:95], v[234:235] op_sel_hi:[1,0]
	v_pk_mul_f32 v[222:223], v[88:89], v[234:235] op_sel_hi:[1,0]
	v_pk_mul_f32 v[224:225], v[90:91], v[234:235] op_sel_hi:[1,0]
	v_pk_fma_f32 v[218:219], v[164:165], v[218:219], v[202:203]
	v_pk_fma_f32 v[220:221], v[166:167], v[220:221], v[204:205]
	v_pk_fma_f32 v[222:223], v[168:169], v[222:223], v[206:207]
	v_pk_fma_f32 v[224:225], v[170:171], v[224:225], v[208:209]
	v_cvt_pk_bf16_f32 v218, v218, v219
	v_cvt_pk_bf16_f32 v219, v220, v221
	v_cvt_pk_bf16_f32 v222, v222, v223
	v_cvt_pk_bf16_f32 v223, v224, v225
	global_store_dwordx2 v21, v[218:219], s[44:45] offset:256
	global_store_dwordx2 v21, v[222:223], s[44:45] offset:288
	s_waitcnt lgkmcnt(3)
	v_add_u32_e32 v20, 0x40000, v31
	v_pk_mul_f32 v[210:211], v[68:69], v[236:237] op_sel_hi:[1,0]
	v_pk_mul_f32 v[212:213], v[70:71], v[236:237] op_sel_hi:[1,0]
	v_pk_mul_f32 v[214:215], v[64:65], v[236:237] op_sel_hi:[1,0]
	v_pk_mul_f32 v[216:217], v[66:67], v[236:237] op_sel_hi:[1,0]
	v_pk_fma_f32 v[210:211], v[150:151], v[210:211], v[172:173]
	v_pk_fma_f32 v[212:213], v[152:153], v[212:213], v[174:175]
	v_pk_fma_f32 v[214:215], v[154:155], v[214:215], v[198:199]
	v_pk_fma_f32 v[216:217], v[156:157], v[216:217], v[200:201]
	v_cvt_pk_bf16_f32 v210, v210, v211
	v_cvt_pk_bf16_f32 v211, v212, v213
	v_cvt_pk_bf16_f32 v214, v214, v215
	v_cvt_pk_bf16_f32 v215, v216, v217
	global_store_dwordx2 v20, v[210:211], s[44:45]
	global_store_dwordx2 v20, v[214:215], s[44:45] offset:32
	v_pk_mul_f32 v[218:219], v[76:77], v[236:237] op_sel_hi:[1,0]
	v_pk_mul_f32 v[220:221], v[78:79], v[236:237] op_sel_hi:[1,0]
	v_pk_mul_f32 v[222:223], v[72:73], v[236:237] op_sel_hi:[1,0]
	v_pk_mul_f32 v[224:225], v[74:75], v[236:237] op_sel_hi:[1,0]
	v_pk_fma_f32 v[218:219], v[164:165], v[218:219], v[202:203]
	v_pk_fma_f32 v[220:221], v[166:167], v[220:221], v[204:205]
	v_pk_fma_f32 v[222:223], v[168:169], v[222:223], v[206:207]
	v_pk_fma_f32 v[224:225], v[170:171], v[224:225], v[208:209]
	v_cvt_pk_bf16_f32 v218, v218, v219
	v_cvt_pk_bf16_f32 v219, v220, v221
	v_cvt_pk_bf16_f32 v222, v222, v223
	v_cvt_pk_bf16_f32 v223, v224, v225
	global_store_dwordx2 v20, v[218:219], s[44:45] offset:256
	global_store_dwordx2 v20, v[222:223], s[44:45] offset:288
	s_waitcnt lgkmcnt(2)
	v_add_u32_e32 v21, 0x48000, v31
	v_pk_mul_f32 v[210:211], v[52:53], v[238:239] op_sel_hi:[1,0]
	v_pk_mul_f32 v[212:213], v[54:55], v[238:239] op_sel_hi:[1,0]
	v_pk_mul_f32 v[214:215], v[48:49], v[238:239] op_sel_hi:[1,0]
	v_pk_mul_f32 v[216:217], v[50:51], v[238:239] op_sel_hi:[1,0]
	v_pk_fma_f32 v[210:211], v[150:151], v[210:211], v[172:173]
	v_pk_fma_f32 v[212:213], v[152:153], v[212:213], v[174:175]
	v_pk_fma_f32 v[214:215], v[154:155], v[214:215], v[198:199]
	v_pk_fma_f32 v[216:217], v[156:157], v[216:217], v[200:201]
	v_cvt_pk_bf16_f32 v210, v210, v211
	v_cvt_pk_bf16_f32 v211, v212, v213
	v_cvt_pk_bf16_f32 v214, v214, v215
	v_cvt_pk_bf16_f32 v215, v216, v217
	global_store_dwordx2 v21, v[210:211], s[44:45]
	global_store_dwordx2 v21, v[214:215], s[44:45] offset:32
	v_pk_mul_f32 v[218:219], v[60:61], v[238:239] op_sel_hi:[1,0]
	v_pk_mul_f32 v[220:221], v[62:63], v[238:239] op_sel_hi:[1,0]
	v_pk_mul_f32 v[222:223], v[56:57], v[238:239] op_sel_hi:[1,0]
	v_pk_mul_f32 v[224:225], v[58:59], v[238:239] op_sel_hi:[1,0]
	v_pk_fma_f32 v[218:219], v[164:165], v[218:219], v[202:203]
	v_pk_fma_f32 v[220:221], v[166:167], v[220:221], v[204:205]
	v_pk_fma_f32 v[222:223], v[168:169], v[222:223], v[206:207]
	v_pk_fma_f32 v[224:225], v[170:171], v[224:225], v[208:209]
	v_cvt_pk_bf16_f32 v218, v218, v219
	v_cvt_pk_bf16_f32 v219, v220, v221
	v_cvt_pk_bf16_f32 v222, v222, v223
	v_cvt_pk_bf16_f32 v223, v224, v225
	global_store_dwordx2 v21, v[218:219], s[44:45] offset:256
	global_store_dwordx2 v21, v[222:223], s[44:45] offset:288
	s_waitcnt lgkmcnt(1)
	v_add_u32_e32 v20, 0x50000, v31
	v_pk_mul_f32 v[210:211], v[44:45], v[240:241] op_sel_hi:[1,0]
	v_pk_mul_f32 v[212:213], v[46:47], v[240:241] op_sel_hi:[1,0]
	v_pk_mul_f32 v[214:215], v[40:41], v[240:241] op_sel_hi:[1,0]
	v_pk_mul_f32 v[216:217], v[42:43], v[240:241] op_sel_hi:[1,0]
	v_pk_fma_f32 v[210:211], v[150:151], v[210:211], v[172:173]
	v_pk_fma_f32 v[212:213], v[152:153], v[212:213], v[174:175]
	v_pk_fma_f32 v[214:215], v[154:155], v[214:215], v[198:199]
	v_pk_fma_f32 v[216:217], v[156:157], v[216:217], v[200:201]
	v_cvt_pk_bf16_f32 v210, v210, v211
	v_cvt_pk_bf16_f32 v211, v212, v213
	v_cvt_pk_bf16_f32 v214, v214, v215
	v_cvt_pk_bf16_f32 v215, v216, v217
	global_store_dwordx2 v20, v[210:211], s[44:45]
	global_store_dwordx2 v20, v[214:215], s[44:45] offset:32
	v_pk_mul_f32 v[218:219], v[36:37], v[240:241] op_sel_hi:[1,0]
	v_pk_mul_f32 v[220:221], v[38:39], v[240:241] op_sel_hi:[1,0]
	v_pk_mul_f32 v[222:223], v[32:33], v[240:241] op_sel_hi:[1,0]
	v_pk_mul_f32 v[224:225], v[34:35], v[240:241] op_sel_hi:[1,0]
	v_pk_fma_f32 v[218:219], v[164:165], v[218:219], v[202:203]
	v_pk_fma_f32 v[220:221], v[166:167], v[220:221], v[204:205]
	v_pk_fma_f32 v[222:223], v[168:169], v[222:223], v[206:207]
	v_pk_fma_f32 v[224:225], v[170:171], v[224:225], v[208:209]
	v_cvt_pk_bf16_f32 v218, v218, v219
	v_cvt_pk_bf16_f32 v219, v220, v221
	v_cvt_pk_bf16_f32 v222, v222, v223
	v_cvt_pk_bf16_f32 v223, v224, v225
	global_store_dwordx2 v20, v[218:219], s[44:45] offset:256
	global_store_dwordx2 v20, v[222:223], s[44:45] offset:288
	s_waitcnt lgkmcnt(0)
	v_add_u32_e32 v21, 0x58000, v31
	v_pk_mul_f32 v[210:211], v[16:17], v[242:243] op_sel_hi:[1,0]
	v_pk_mul_f32 v[212:213], v[18:19], v[242:243] op_sel_hi:[1,0]
	v_pk_mul_f32 v[214:215], v[12:13], v[242:243] op_sel_hi:[1,0]
	v_pk_mul_f32 v[216:217], v[14:15], v[242:243] op_sel_hi:[1,0]
	v_pk_fma_f32 v[210:211], v[150:151], v[210:211], v[172:173]
	v_pk_fma_f32 v[212:213], v[152:153], v[212:213], v[174:175]
	v_pk_fma_f32 v[214:215], v[154:155], v[214:215], v[198:199]
	v_pk_fma_f32 v[216:217], v[156:157], v[216:217], v[200:201]
	v_cvt_pk_bf16_f32 v210, v210, v211
	v_cvt_pk_bf16_f32 v211, v212, v213
	v_cvt_pk_bf16_f32 v214, v214, v215
	v_cvt_pk_bf16_f32 v215, v216, v217
	global_store_dwordx2 v21, v[210:211], s[44:45]
	global_store_dwordx2 v21, v[214:215], s[44:45] offset:32
	v_pk_mul_f32 v[218:219], v[8:9], v[242:243] op_sel_hi:[1,0]
	v_pk_mul_f32 v[220:221], v[10:11], v[242:243] op_sel_hi:[1,0]
	v_pk_mul_f32 v[222:223], v[0:1], v[242:243] op_sel_hi:[1,0]
	v_pk_mul_f32 v[224:225], v[2:3], v[242:243] op_sel_hi:[1,0]
	v_pk_fma_f32 v[218:219], v[164:165], v[218:219], v[202:203]
	v_pk_fma_f32 v[220:221], v[166:167], v[220:221], v[204:205]
	v_pk_fma_f32 v[222:223], v[168:169], v[222:223], v[206:207]
	v_pk_fma_f32 v[224:225], v[170:171], v[224:225], v[208:209]
	v_cvt_pk_bf16_f32 v218, v218, v219
	v_cvt_pk_bf16_f32 v219, v220, v221
	v_cvt_pk_bf16_f32 v222, v222, v223
	v_cvt_pk_bf16_f32 v223, v224, v225
	global_store_dwordx2 v21, v[218:219], s[44:45] offset:256
	global_store_dwordx2 v21, v[222:223], s[44:45] offset:288
	s_add_i32 s17, s17, s16
	s_cmpk_gt_i32 s17, 0xff
	s_waitcnt vmcnt(0)
	s_cbranch_scc1 .LBB0_74
